# ret_u second round skips the per-unit decay-rate header (addresses only)
# speedup vs baseline: 1.0126x; 1.0018x over previous
.LBB0_469:
	s_cmp_eq_u32 s101, 0
	s_cbranch_scc1 .Lru_hdr
	v_and_b32_e32 v0, 0xffffff80, v143
	v_ashrrev_i32_e32 v1, 31, v0
	v_lshlrev_b64 v[0:1], 1, v[0:1]
	v_readlane_b32 s6, v253, 56
	v_readlane_b32 s7, v253, 57
	v_lshl_add_u64 v[94:95], v[90:91], 0, v[0:1]
	s_and_b32 s0, s101, 0xff
	v_lshl_add_u64 v[100:101], v[92:93], 0, v[0:1]
	s_mov_b64 s[8:9], 0
	v_lshlrev_b32_e32 v2, 1, v122
	v_ashrrev_i32_e32 v3, 31, v2
	v_lshlrev_b64 v[4:5], 14, v[2:3]
	v_or_b32_e32 v2, 1, v2
	v_ashrrev_i32_e32 v3, 31, v2
	v_lshlrev_b64 v[2:3], 14, v[2:3]
	v_lshl_add_u64 v[96:97], s[6:7], 0, v[4:5]
	v_lshl_add_u64 v[98:99], s[6:7], 0, v[2:3]
	s_branch .LBB0_470
